# speedup vs baseline: 1.0670x; 1.0154x over previous
; __device__ __forceinline__ int v_st(int k, int c) { const int kk = (k & ~0xC) | ((k & 4) << 1) | ((k & 8) >> 1); return ((kk >> 3) * 4 + (c >> 5)) * 512 + ((kk & 7) * 32 + (c & 31)) * 2; }
; __device__ __forceinline__ int v_rd_base(int lane) { return ((lane & 3) << 3) | (((lane >> 2) & 3) << 6) | (((lane >> 4) & 1) << 5) | (((lane >> 5) & 1) << 8); }
; #define SWRITE(b, i) do { *(bf16x8*)((char*)V_lds + (b) * SHM_V + vst) = sr_[i].v; \
;     *(bf16x8*)((char*)K_lds + (b) * SHM_K + ksw0) = sr_[i].k0; \
;     if (k2) *(bf16x8*)((char*)K_lds + (b) * SHM_K + ksw1) = sr_[i].k1; } while (0)
; template <int DQK, bool FIX>
; __device__ __forceinline__ void attn_item(const bf16* Qb, const bf16* __restrict__ Kh, const bf16* __restrict__ Vh,
;                                           u16* Ob, int q0, int L, int NT, char* lds, float mC) {
;     ...
;   int tid = threadIdx.x; asm volatile("" : "+v"(tid));
;   const int wid = tid >> 6, lane = tid & 63, r32 = lane & 31, hi = lane >> 5;
;   bf16* V_lds = (bf16*)lds; bf16* K_lds = (bf16*)(lds + 2 * SHM_V);
;   float* ws = (float*)(lds + 2 * SHM_V + 2 * SHM_K) + wid * 64; float* li_l = ws; float* al_l = ws + 32;
;   float m_reg = -1e30f, l_reg = 0; f32x16 o[2] = {}; bf16x8 qr[ND];
;   __syncthreads();
;   { int qrow = q0 + wid * 32 + r32; if (qrow > L - 1) qrow = L - 1;
;     const bf16* Qw = Qb + (long)qrow * ldq + hi * 8;
; #pragma unroll
;     for (int d0 = 0; d0 < ND; ++d0) qr[d0] = *reinterpret_cast<const bf16x8*>(Qw + d0 * 16); }
;   const int vr = tid >> 3, vc = (tid & 7) * 8, vst = v_st(vr, vc);
;   const int kr0 = tid / KCH, kc0 = (tid % KCH) * 8, kr1 = (tid + 512) / KCH, kc1 = ((tid + 512) % KCH) * 8;
;   const bool k2 = (DQK == 96) && (tid < 256);
;   const int ksw0 = KSWZ(kr0, kc0 * 2), ksw1 = KSWZ(kr1, kc1 * 2);
;   const int vb0 = (int)(uintptr_t)V_lds + v_rd_base(lane);
;   struct { bf16x8 v, k0, k1; } sr_[2];
;     ...
;   f32x16 pA0, pA1, pB0, pB1; float mnA = 0.f, mnB = 0.f, alA = 1.f, alB = 1.f; bf16x8 pa0, pa1, pa2, pa3;
;   constexpr int SE = 0, SO = 1;
;   const bool act = (q0 + wid * 32) < L;
;   SLOAD(SE, 0); asm volatile("s_waitcnt vmcnt(0)" ::: "memory"); SWRITE(0, SE); __syncthreads();
;   if (act) { qkt<DQK>(pA0, pA1, K_lds, qr, r32, hi, 0, L); partialSM<DQK, FIX>(pA0, pA1, m_reg, mnA, alA, mC); }
;   SLOAD(SO, KVBLK); if (2 < NT) SLOAD(SE, 2 * KVBLK);
;   SWAIT(); SWRITE(1, SO); __syncthreads();
.LBB0_822:
	s_ashr_i32 s19, s4, 1
	s_and_b32 s18, s4, 3
	s_and_b32 s6, s19, -2
	s_cmp_gt_u32 s18, 1
	s_mov_b64 s[2:3], -1
	s_cbranch_scc0 .LBB0_866
	v_writelane_b32 v254, s6, 61
	s_add_i32 s2, s18, s6
	s_add_i32 s4, s2, -2
	s_lshl_b64 s[2:3], s[82:83], 10
	v_readlane_b32 s5, v254, 41
	s_add_u32 s5, s5, s2
	v_readlane_b32 s2, v254, 42
	s_addc_u32 s6, s2, s3
	s_lshl_b32 s2, s4, 6
	s_ashr_i32 s3, s2, 31
	s_lshl_b64 s[2:3], s[2:3], 1
	s_add_u32 s10, s5, s2
	s_addc_u32 s11, s6, s3
	s_lshl_b64 s[6:7], s[82:83], 8
	v_readlane_b32 s2, v254, 49
	s_add_u32 s8, s2, s6
	v_readlane_b32 s2, v254, 50
	s_addc_u32 s9, s2, s7
	s_lshl_b32 s2, s4, 4
	s_andn2_b32 s2, s2, 63
	s_ashr_i32 s3, s2, 31
	s_lshl_b64 s[4:5], s[2:3], 1
	s_add_u32 s12, s8, s4
	s_addc_u32 s13, s9, s5
	v_readlane_b32 s2, v254, 43
	s_add_u32 s2, s2, s6
	v_readlane_b32 s3, v254, 44
	s_addc_u32 s3, s3, s7
	s_add_u32 s14, s2, s4
	v_mov_b32_e32 v158, v165
	s_addc_u32 s15, s3, s5
	s_lshl_b32 s2, s16, 8
	v_writelane_b32 v254, s10, 62
	v_ashrrev_i32_e32 v157, 6, v158
	v_and_b32_e32 v156, 31, v158
	v_lshl_add_u32 v154, v157, 5, s2
	v_or_b32_e32 v0, v154, v156
	s_add_i32 s2, s96, -1
	v_min_i32_e32 v2, s2, v0
	v_ashrrev_i32_e32 v3, 31, v2
	v_bfe_u32 v155, v158, 5, 1
	v_lshlrev_b64 v[2:3], 10, v[2:3]
	v_lshl_add_u64 v[4:5], s[10:11], 0, v[2:3]
	v_lshlrev_b32_e32 v2, 4, v155
	v_mov_b32_e32 v3, v1
	v_lshl_add_u64 v[4:5], v[4:5], 0, v[2:3]
	v_ashrrev_i32_e32 v18, 3, v158
	s_waitcnt lgkmcnt(0)
	s_barrier
	global_load_dwordx4 v[98:101], v[4:5], off
	global_load_dwordx4 v[102:105], v[4:5], off offset:32
	global_load_dwordx4 v[106:109], v[4:5], off offset:64
	global_load_dwordx4 v[110:113], v[4:5], off offset:96
	v_and_b32_e32 v3, 0xfffff8, v18
	v_lshlrev_b32_e32 v4, 1, v18
	v_lshlrev_b32_e32 v0, 3, v158
	v_and_or_b32 v3, v4, 0, v3
	v_and_b32_e32 v6, 56, v0
	v_lshrrev_b32_e32 v3, 1, v3
	v_bfe_u32 v0, v0, 5, 1
	v_lshrrev_b32_e32 v4, 1, v18
	v_or_b32_e32 v0, v3, v0
	v_and_b32_e32 v3, 7, v18
	v_and_or_b32 v4, v4, 0, v3
	v_lshlrev_b32_e32 v3, 4, v158
	v_and_b32_e32 v5, 48, v3
	v_lshl_or_b32 v4, v4, 6, v5
	v_lshl_or_b32 v0, v0, 9, v4
	v_ashrrev_i32_e32 v4, 31, v158
	v_lshrrev_b32_e32 v4, 29, v4
	v_add_u32_e32 v4, v158, v4
	v_ashrrev_i32_e32 v22, 3, v4
	v_and_b32_e32 v4, -8, v4
	v_sub_u32_e32 v4, v158, v4
	v_ashrrev_i32_e32 v19, 31, v18
	v_ashrrev_i32_e32 v23, 31, v22
	v_lshlrev_b32_e32 v26, 3, v4
	v_lshlrev_b32_e32 v5, 8, v22
	v_bitop3_b32 v4, v22, v4, 15 bitop3:0x6c
	v_lshlrev_b64 v[20:21], 8, v[18:19]
	v_lshlrev_b64 v[24:25], 8, v[22:23]
	v_lshl_add_u32 v12, v4, 4, v5
	v_lshl_add_u64 v[4:5], s[14:15], 0, v[20:21]
	v_lshlrev_b32_e32 v28, 1, v6
	v_mov_b32_e32 v29, v1
	v_ashrrev_i32_e32 v27, 31, v26
	v_lshl_add_u64 v[8:9], s[12:13], 0, v[24:25]
	v_lshl_add_u64 v[4:5], v[4:5], 0, v[28:29]
	v_lshl_add_u64 v[8:9], v[26:27], 1, v[8:9]
	global_load_dwordx4 v[4:7], v[4:5], off
	v_add_u32_e32 v160, 0, v0
	global_load_dwordx4 v[8:11], v[8:9], off
	s_waitcnt vmcnt(0)
	v_and_b32_e32 v0, 0x70, v3
	v_and_b32_e32 v209, 0xf0, v3
	s_movk_i32 s2, 0x60
	v_writelane_b32 v254, s11, 63
	v_cmp_gt_i32_e64 s[8:9], s96, v154
	v_cmp_le_i32_e32 vcc, s96, v154
	v_add_u32_e32 v161, 0, v12
	v_bitop3_b32 v31, v2, v209, 32 bitop3:0x36
	v_bitop3_b32 v32, v2, v209, 64 bitop3:0x36
	v_bitop3_b32 v33, v2, v209, s2 bitop3:0x36
	s_waitcnt vmcnt(1)
	ds_write_b128 v160, v[4:7]
	s_waitcnt vmcnt(0)
	ds_write_b128 v161, v[8:11] offset:32768
	s_waitcnt lgkmcnt(0)
	s_barrier
	s_and_saveexec_b64 s[2:3], vcc
	s_xor_b64 s[2:3], exec, s[2:3]
	s_movk_i32 s10, 0x60
	v_bitop3_b32 v31, v2, v209, 32 bitop3:0x36
	v_bitop3_b32 v32, v2, v209, 64 bitop3:0x36
	v_bitop3_b32 v33, v2, v209, s10 bitop3:0x36
	s_or_saveexec_b64 s[2:3], s[2:3]
	s_movk_i32 s10, 0xf0
	v_bitop3_b32 v66, v2, v3, s10 bitop3:0x78
	v_readlane_b32 s10, v254, 53
	v_readlane_b32 s11, v254, 54
	v_lshlrev_b32_e32 v30, 8, v156
	s_nop 0
	v_cndmask_b32_e64 v2, 0, 1, s[10:11]
	v_cmp_ne_u32_e64 s[10:11], 1, v2
	s_xor_b64 exec, exec, s[2:3]
	s_cbranch_execz .LBB0_829
	v_add3_u32 v29, 0, v66, v30
	ds_read_b128 v[2:5], v29 offset:32768
	ds_read_b128 v[34:37], v29 offset:40960
	v_add3_u32 v29, 0, v31, v30
	ds_read_b128 v[50:53], v29 offset:32768
	s_and_b64 vcc, exec, s[10:11]
	s_waitcnt lgkmcnt(2)
	v_mfma_f32_32x32x16_bf16 v[2:17], v[2:5], v[98:101], 0
	s_waitcnt lgkmcnt(0)
	v_mfma_f32_32x32x16_bf16 v[2:17], v[50:53], v[102:105], v[2:17]
	ds_read_b128 v[50:53], v29 offset:40960
	v_add3_u32 v29, 0, v32, v30
	v_mfma_f32_32x32x16_bf16 v[34:49], v[34:37], v[98:101], 0
	s_waitcnt lgkmcnt(0)
	v_mfma_f32_32x32x16_bf16 v[34:49], v[50:53], v[102:105], v[34:49]
	ds_read_b128 v[50:53], v29 offset:32768
	s_waitcnt lgkmcnt(0)
	v_mfma_f32_32x32x16_bf16 v[2:17], v[50:53], v[106:109], v[2:17]
	ds_read_b128 v[50:53], v29 offset:40960
	v_add3_u32 v29, 0, v33, v30
	s_waitcnt lgkmcnt(0)
	v_mfma_f32_32x32x16_bf16 v[34:49], v[50:53], v[106:109], v[34:49]
	ds_read_b128 v[50:53], v29 offset:32768
	s_waitcnt lgkmcnt(0)
	v_mfma_f32_32x32x16_bf16 v[2:17], v[50:53], v[110:113], v[2:17]
	ds_read_b128 v[50:53], v29 offset:40960
	s_waitcnt lgkmcnt(0)
	v_mfma_f32_32x32x16_bf16 v[34:49], v[50:53], v[110:113], v[34:49]
	s_cbranch_vccnz .LBB0_828
	s_nop 7
	v_sub_f32_e32 v17, v17, v174
	v_sub_f32_e32 v16, v16, v174
	v_sub_f32_e32 v15, v15, v174
	v_sub_f32_e32 v14, v14, v174
	v_sub_f32_e32 v13, v13, v174
	v_sub_f32_e32 v12, v12, v174
	v_sub_f32_e32 v11, v11, v174
	v_sub_f32_e32 v10, v10, v174
	v_sub_f32_e32 v9, v9, v174
	v_sub_f32_e32 v8, v8, v174
	v_sub_f32_e32 v7, v7, v174
	v_sub_f32_e32 v6, v6, v174
	v_sub_f32_e32 v5, v5, v174
	v_sub_f32_e32 v4, v4, v174
	v_sub_f32_e32 v3, v3, v174
	v_sub_f32_e32 v2, v2, v174
	v_sub_f32_e32 v49, v49, v174
	v_sub_f32_e32 v48, v48, v174
	v_sub_f32_e32 v47, v47, v174
	v_sub_f32_e32 v46, v46, v174
	v_sub_f32_e32 v45, v45, v174
	v_sub_f32_e32 v44, v44, v174
	v_sub_f32_e32 v43, v43, v174
	v_sub_f32_e32 v42, v42, v174
	v_sub_f32_e32 v41, v41, v174
	v_sub_f32_e32 v40, v40, v174
	v_sub_f32_e32 v39, v39, v174
	v_sub_f32_e32 v38, v38, v174
	v_sub_f32_e32 v37, v37, v174
	v_sub_f32_e32 v36, v36, v174
	v_sub_f32_e32 v35, v35, v174
	v_sub_f32_e32 v34, v34, v174

; __device__ __forceinline__ int crow(int r, int hi) { return (r & 3) + 8 * (r >> 2) + 4 * hi; }
; __device__ __forceinline__ int v_st(int k, int c) { const int kk = (k & ~0xC) | ((k & 4) << 1) | ((k & 8) >> 1); return ((kk >> 3) * 4 + (c >> 5)) * 512 + ((kk & 7) * 32 + (c & 31)) * 2; }
; __device__ __forceinline__ int v_rd_base(int lane) { return ((lane & 3) << 3) | (((lane >> 2) & 3) << 6) | (((lane >> 4) & 1) << 5) | (((lane >> 5) & 1) << 8); }
; template <int DQK>
; __device__ __forceinline__ void qkt(f32x16& p0, f32x16& p1, const bf16* Ks, const bf16x8* qr, int r32, int hi, int k0, int L) {
;   p0 = f32x16{}; p1 = f32x16{};
; #pragma unroll
;   for (int d0 = 0; d0 < DQK / 16; ++d0) { int cb = (d0 * 16 + hi * 8) * 2;
;     bf16x8 b0 = *reinterpret_cast<const bf16x8*>((const char*)Ks + KSWZ(r32, cb));
;     bf16x8 b1 = *reinterpret_cast<const bf16x8*>((const char*)Ks + KSWZ(32 + r32, cb));
;     p0 = __builtin_amdgcn_mfma_f32_32x32x16_bf16(b0, qr[d0], p0, 0, 0, 0);
;     p1 = __builtin_amdgcn_mfma_f32_32x32x16_bf16(b1, qr[d0], p1, 0, 0, 0); }
;   if (k0 + KVBLK > L) {
; #pragma unroll
;     for (int r = 0; r < 16; ++r) { const int key = k0 + crow(r, hi);
;       if (key >= L) p0[r] = -1e30f;
;       if (key + 32 >= L) p1[r] = -1e30f; }
;   }
; template <int DQK, bool FIX>
; __device__ __forceinline__ void attn_item(const bf16* Qb, const bf16* __restrict__ Kh, const bf16* __restrict__ Vh,
;                                           u16* Ob, int q0, int L, int NT, char* lds, float mC) {
;     ...
;   const int vr = tid >> 3, vc = (tid & 7) * 8, vst = v_st(vr, vc);
;   const int kr0 = tid / KCH, kc0 = (tid % KCH) * 8, kr1 = (tid + 512) / KCH, kc1 = ((tid + 512) % KCH) * 8;
;   const bool k2 = (DQK == 96) && (tid < 256);
;   const int ksw0 = KSWZ(kr0, kc0 * 2), ksw1 = KSWZ(kr1, kc1 * 2);
;   const int vb0 = (int)(uintptr_t)V_lds + v_rd_base(lane);
;   struct { bf16x8 v, k0, k1; } sr_[2];
;     ...
;   f32x16 pA0, pA1, pB0, pB1; float mnA = 0.f, mnB = 0.f, alA = 1.f, alB = 1.f; bf16x8 pa0, pa1, pa2, pa3;
;   constexpr int SE = 0, SO = 1;
;   const bool act = (q0 + wid * 32) < L;
;   SLOAD(SE, 0); asm volatile("s_waitcnt vmcnt(0)" ::: "memory"); SWRITE(0, SE); __syncthreads();
;   if (act) { qkt<DQK>(pA0, pA1, K_lds, qr, r32, hi, 0, L); partialSM<DQK, FIX>(pA0, pA1, m_reg, mnA, alA, mC); }
.LBB0_869:
	s_or_b64 exec, exec, s[10:11]
	v_and_b32_e32 v13, 0xfffff8, v24
	v_lshlrev_b32_e32 v14, 1, v24
	v_and_or_b32 v13, v14, 0, v13
	v_lshrrev_b32_e32 v13, 1, v13
	v_lshrrev_b32_e32 v11, 5, v11
	v_lshrrev_b32_e32 v14, 1, v24
	v_or_b32_e32 v11, v13, v11
	v_and_b32_e32 v13, 7, v24
	v_and_or_b32 v13, v14, 0, v13
	v_and_b32_e32 v14, 48, v26
	v_lshl_or_b32 v13, v13, 6, v14
	v_lshl_or_b32 v11, v11, 9, v13
	v_lshlrev_b32_e32 v13, 8, v30
	v_bitop3_b32 v10, v30, v10, 15 bitop3:0x6c
	v_lshl_add_u32 v10, v10, 4, v13
	v_lshlrev_b32_e32 v13, 8, v28
	v_bitop3_b32 v12, v28, v12, 15 bitop3:0x6c
	s_waitcnt vmcnt(0)
	v_lshl_add_u32 v12, v12, 4, v13
	v_add_u32_e32 v193, 0, v11
	v_add_u32_e32 v194, 0, v10
	v_add_u32_e32 v195, 0, v12
	s_waitcnt vmcnt(1)
	ds_write_b128 v193, v[2:5]
	s_waitcnt vmcnt(0)
	ds_write_b128 v194, v[6:9] offset:32768
	s_and_saveexec_b64 s[10:11], s[8:9]
	ds_write_b128 v195, v[136:139] offset:32768
	s_or_b64 exec, exec, s[10:11]
	v_readlane_b32 s4, v254, 55
	v_readlane_b32 s5, v254, 56
	v_cmp_gt_i32_e64 s[10:11], s96, v175
	v_lshlrev_b32_e32 v29, 8, v190
	v_cndmask_b32_e64 v2, 0, 1, s[4:5]
	v_lshlrev_b32_e32 v31, 4, v190
	v_cmp_ne_u32_e64 s[12:13], 1, v2
	s_waitcnt lgkmcnt(0)
	s_barrier
	s_and_saveexec_b64 s[16:17], s[10:11]
	s_cbranch_execz .LBB0_875
	s_movk_i32 s4, 0xf0
	v_bitop3_b32 v2, v0, v31, s4 bitop3:0x78
	v_add3_u32 v27, 0, v2, v29
	ds_read_b128 v[2:5], v27 offset:32768
	ds_read_b128 v[32:35], v27 offset:40960
	v_and_b32_e32 v27, 0xf0, v31
	s_movk_i32 s4, 0x60
	s_and_b64 vcc, exec, s[12:13]
	s_waitcnt lgkmcnt(0)
	v_mfma_f32_32x32x16_bf16 v[48:63], v[32:35], v[112:115], 0
	v_bitop3_b32 v32, v0, v27, 32 bitop3:0x36
	v_add3_u32 v36, 0, v32, v29
	ds_read_b128 v[32:35], v36 offset:32768
	v_mfma_f32_32x32x16_bf16 v[2:17], v[2:5], v[112:115], 0
	s_waitcnt lgkmcnt(0)
	v_mfma_f32_32x32x16_bf16 v[2:17], v[32:35], v[116:119], v[2:17]
	ds_read_b128 v[32:35], v36 offset:40960
	s_waitcnt lgkmcnt(0)
	v_mfma_f32_32x32x16_bf16 v[48:63], v[32:35], v[116:119], v[48:63]
	v_bitop3_b32 v32, v0, v27, 64 bitop3:0x36
	v_add3_u32 v36, 0, v32, v29
	ds_read_b128 v[32:35], v36 offset:32768
	s_waitcnt lgkmcnt(0)
	v_mfma_f32_32x32x16_bf16 v[2:17], v[32:35], v[120:123], v[2:17]
	ds_read_b128 v[32:35], v36 offset:40960
	s_waitcnt lgkmcnt(0)
	v_mfma_f32_32x32x16_bf16 v[48:63], v[32:35], v[120:123], v[48:63]
	v_bitop3_b32 v32, v0, v27, s4 bitop3:0x36
	v_add3_u32 v36, 0, v32, v29
	ds_read_b128 v[32:35], v36 offset:32768
	s_movk_i32 s4, 0x80
	s_waitcnt lgkmcnt(0)
	v_mfma_f32_32x32x16_bf16 v[2:17], v[32:35], v[124:127], v[2:17]
	ds_read_b128 v[32:35], v36 offset:40960
	s_waitcnt lgkmcnt(0)
	v_mfma_f32_32x32x16_bf16 v[48:63], v[32:35], v[124:127], v[48:63]
	v_bitop3_b32 v32, v0, v27, s4 bitop3:0x36
	v_add3_u32 v36, 0, v32, v29
	ds_read_b128 v[32:35], v36 offset:32768
	s_movk_i32 s4, 0xa0
	v_bitop3_b32 v27, v0, v27, s4 bitop3:0x36
	v_add3_u32 v27, 0, v27, v29
	s_waitcnt lgkmcnt(0)
	v_mfma_f32_32x32x16_bf16 v[2:17], v[32:35], v[128:131], v[2:17]
	ds_read_b128 v[32:35], v36 offset:40960
	s_waitcnt lgkmcnt(0)
	v_mfma_f32_32x32x16_bf16 v[48:63], v[32:35], v[128:131], v[48:63]
	ds_read_b128 v[32:35], v27 offset:32768
	s_waitcnt lgkmcnt(0)
	v_mfma_f32_32x32x16_bf16 v[2:17], v[32:35], v[132:135], v[2:17]
	ds_read_b128 v[32:35], v27 offset:40960
	s_waitcnt lgkmcnt(0)
	v_mfma_f32_32x32x16_bf16 v[48:63], v[32:35], v[132:135], v[48:63]
	s_cbranch_vccnz .LBB0_874
	s_nop 7
	v_sub_f32_e32 v17, v17, v173
	v_sub_f32_e32 v16, v16, v173
	v_sub_f32_e32 v15, v15, v173
	v_sub_f32_e32 v14, v14, v173
	v_sub_f32_e32 v13, v13, v173
	v_sub_f32_e32 v12, v12, v173
	v_sub_f32_e32 v11, v11, v173
	v_sub_f32_e32 v10, v10, v173
	v_sub_f32_e32 v9, v9, v173
	v_sub_f32_e32 v8, v8, v173
	v_sub_f32_e32 v7, v7, v173
	v_sub_f32_e32 v6, v6, v173
	v_sub_f32_e32 v5, v5, v173
	v_sub_f32_e32 v4, v4, v173
	v_sub_f32_e32 v3, v3, v173
	v_sub_f32_e32 v2, v2, v173
	v_sub_f32_e32 v63, v63, v173
	v_sub_f32_e32 v62, v62, v173
	v_sub_f32_e32 v61, v61, v173
	v_sub_f32_e32 v60, v60, v173
	v_sub_f32_e32 v59, v59, v173
	v_sub_f32_e32 v58, v58, v173
	v_sub_f32_e32 v57, v57, v173
	v_sub_f32_e32 v56, v56, v173
	v_sub_f32_e32 v55, v55, v173
	v_sub_f32_e32 v54, v54, v173
	v_sub_f32_e32 v53, v53, v173
	v_sub_f32_e32 v52, v52, v173
	v_sub_f32_e32 v51, v51, v173
	v_sub_f32_e32 v50, v50, v173
	v_sub_f32_e32 v49, v49, v173
	v_sub_f32_e32 v48, v48, v173

; __device__ __forceinline__ int v_st(int k, int c) { const int kk = (k & ~0xC) | ((k & 4) << 1) | ((k & 8) >> 1); return ((kk >> 3) * 4 + (c >> 5)) * 512 + ((kk & 7) * 32 + (c & 31)) * 2; }
; __device__ __forceinline__ int v_rd_base(int lane) { return ((lane & 3) << 3) | (((lane >> 2) & 3) << 6) | (((lane >> 4) & 1) << 5) | (((lane >> 5) & 1) << 8); }
; #define SLOAD(i, key0) do { sr_[i].v = *reinterpret_cast<const bf16x8*>(&Vh[(long)((key0) + vr) * ldv + vc]); \
;     sr_[i].k0 = *reinterpret_cast<const bf16x8*>(&Kh[(long)((key0) + kr0) * ldk + kc0]); \
;     if (k2) sr_[i].k1 = *reinterpret_cast<const bf16x8*>(&Kh[(long)((key0) + kr1) * ldk + kc1]); } while (0)
; #define SWRITE(b, i) do { *(bf16x8*)((char*)V_lds + (b) * SHM_V + vst) = sr_[i].v; \
;     *(bf16x8*)((char*)K_lds + (b) * SHM_K + ksw0) = sr_[i].k0; \
;     if (k2) *(bf16x8*)((char*)K_lds + (b) * SHM_K + ksw1) = sr_[i].k1; } while (0)
; template <int DQK, bool FIX>
; __device__ __forceinline__ void attn_item(const bf16* Qb, const bf16* __restrict__ Kh, const bf16* __restrict__ Vh,
;                                           u16* Ob, int q0, int L, int NT, char* lds, float mC) {
;     ...
;   float m_reg = -1e30f, l_reg = 0; f32x16 o[2] = {}; bf16x8 qr[ND];
;   __syncthreads();
;   { int qrow = q0 + wid * 32 + r32; if (qrow > L - 1) qrow = L - 1;
;     const bf16* Qw = Qb + (long)qrow * ldq + hi * 8;
; #pragma unroll
;     for (int d0 = 0; d0 < ND; ++d0) qr[d0] = *reinterpret_cast<const bf16x8*>(Qw + d0 * 16); }
;   const int vr = tid >> 3, vc = (tid & 7) * 8, vst = v_st(vr, vc);
;   const int kr0 = tid / KCH, kc0 = (tid % KCH) * 8, kr1 = (tid + 512) / KCH, kc1 = ((tid + 512) % KCH) * 8;
;   const bool k2 = (DQK == 96) && (tid < 256);
;   const int ksw0 = KSWZ(kr0, kc0 * 2), ksw1 = KSWZ(kr1, kc1 * 2);
;   const int vb0 = (int)(uintptr_t)V_lds + v_rd_base(lane);
;   struct { bf16x8 v, k0, k1; } sr_[2];
;     ...
;   f32x16 pA0, pA1, pB0, pB1; float mnA = 0.f, mnB = 0.f, alA = 1.f, alB = 1.f; bf16x8 pa0, pa1, pa2, pa3;
;   constexpr int SE = 0, SO = 1;
;   const bool act = (q0 + wid * 32) < L;
;   SLOAD(SE, 0); asm volatile("s_waitcnt vmcnt(0)" ::: "memory"); SWRITE(0, SE); __syncthreads();
;   if (act) { qkt<DQK>(pA0, pA1, K_lds, qr, r32, hi, 0, L); partialSM<DQK, FIX>(pA0, pA1, m_reg, mnA, alA, mC); }
;   SLOAD(SO, KVBLK); if (2 < NT) SLOAD(SE, 2 * KVBLK);
;   SWAIT(); SWRITE(1, SO); __syncthreads();
.LBB0_879:
	s_or_b64 exec, exec, s[6:7]
	s_waitcnt vmcnt(2)
	s_waitcnt vmcnt(3)
	ds_write_b128 v193, v[2:5] offset:16384
	s_waitcnt vmcnt(2)
	ds_write_b128 v194, v[6:9] offset:49152
	s_and_saveexec_b64 s[2:3], s[8:9]
	ds_write_b128 v195, v[140:143] offset:49152
	s_or_b64 exec, exec, s[2:3]
	v_lshlrev_b32_e32 v3, 4, v192
	v_lshlrev_b32_e32 v2, 3, v192
	v_and_b32_e32 v3, 0xc0, v3
	v_lshlrev_b32_e32 v4, 1, v192
	v_and_or_b32 v3, v2, 24, v3
	v_and_b32_e32 v4, 32, v4
	v_and_b32_e32 v2, 0x100, v2
	s_cmp_lg_u32 0, -1
	v_or3_b32 v2, v3, v4, v2
	s_cselect_b32 s2, 0, 0
	v_add_u32_e32 v197, s2, v2
	s_addk_i32 s2, 0x4000
	s_lshr_b32 s16, s19, 1
	v_and_b32_e32 v3, 0xf0, v31
	v_or_b32_e32 v4, 32, v0
	v_add_u32_e32 v199, s2, v2
	s_mul_i32 s2, s16, 0xc0
	s_mul_i32 s3, s18, 0x60
	v_xad_u32 v17, v4, v3, 0
	v_or_b32_e32 v4, 64, v0
	s_add_i32 s2, s2, s3
	v_xad_u32 v24, v4, v3, 0
	v_or_b32_e32 v4, 0x60, v0
	s_ashr_i32 s3, s2, 31
	v_xad_u32 v16, v0, v3, 0
	v_xad_u32 v25, v4, v3, 0
	v_or_b32_e32 v4, 0x80, v0
	v_or_b32_e32 v0, 0xa0, v0
	s_lshl_b64 s[6:7], s[2:3], 1
	s_mul_hi_u32 s2, s82, 0x600
	s_mul_i32 s3, s82, 0x600
	v_xad_u32 v26, v4, v3, 0
	v_xad_u32 v27, v0, v3, 0
	v_mov_b32_e32 v2, s3
	v_mov_b32_e32 v3, s2
	v_mad_i64_i32 v[2:3], s[2:3], v28, s65, v[2:3]
	v_readlane_b32 s20, v254, 35
	v_lshl_add_u64 v[2:3], v[22:23], 1, v[2:3]
	v_readlane_b32 s21, v254, 36
	s_sub_i32 s5, s96, 64
	s_sub_i32 s78, s96, 32
	v_lshl_add_u64 v[166:167], s[20:21], 0, v[2:3]
	v_mad_u64_u32 v[2:3], s[2:3], s82, v185, v[10:11]
	s_lshl_b32 s2, s16, 7
	s_lshl_b32 s3, s18, 6
	s_add_i32 s2, s2, s3
	v_lshl_add_u64 v[2:3], v[18:19], 1, v[2:3]
	s_ashr_i32 s3, s2, 31
	v_lshl_add_u64 v[168:169], s[20:21], 0, v[2:3]
	v_lshl_add_u64 v[2:3], v[20:21], 0, s[14:15]
	v_and_b32_e32 v0, 7, v176
	s_lshl_b64 s[2:3], s[2:3], 1
	v_readlane_b32 s14, v254, 57
	v_lshlrev_b32_e32 v0, 4, v0
	s_add_u32 s2, s14, s2
	v_readlane_b32 s14, v254, 58
	v_lshl_add_u64 v[2:3], v[2:3], 0, v[0:1]
	s_addc_u32 s3, s14, s3
	v_mov_b32_e32 v14, v1
	v_mov_b32_e32 v15, v1
	v_lshl_add_u64 v[170:171], s[2:3], 0, v[2:3]
	v_mov_b32_e32 v0, v1
	v_mov_b32_e32 v2, v1
	v_mov_b32_e32 v3, v1
	v_mov_b32_e32 v4, v1
	v_mov_b32_e32 v5, v1
	v_mov_b32_e32 v6, v1
	v_mov_b32_e32 v7, v1
	v_mov_b32_e32 v8, v1
	v_mov_b32_e32 v9, v1
	v_mov_b32_e32 v10, v1
	v_mov_b32_e32 v11, v1
	v_mov_b32_e32 v12, v1
	v_mov_b32_e32 v13, v1
	v_add_u32_e32 v200, v16, v29
	v_add_u32_e32 v201, v17, v29
	v_add_u32_e32 v202, v24, v29
	v_add_u32_e32 v203, v25, v29
	v_add_u32_e32 v204, v26, v29
	v_add_u32_e32 v205, v27, v29
	v_mov_b64_e32 v[46:47], v[14:15]
	v_mov_b64_e32 v[30:31], v[14:15]
	v_mov_b64_e32 v[94:95], v[14:15]
	v_mov_b64_e32 v[110:111], v[14:15]
	s_mov_b32 s79, 4
	s_mov_b32 s4, 0
	v_lshlrev_b32_e32 v196, 2, v189
	v_mov_b32_e32 v198, 0
	v_mov_b64_e32 v[44:45], v[12:13]
	v_mov_b64_e32 v[42:43], v[10:11]
	v_mov_b64_e32 v[40:41], v[8:9]
	v_mov_b64_e32 v[38:39], v[6:7]
	v_mov_b64_e32 v[36:37], v[4:5]
	v_mov_b64_e32 v[34:35], v[2:3]
	v_mov_b64_e32 v[32:33], v[0:1]
	v_mov_b64_e32 v[28:29], v[12:13]
	v_mov_b64_e32 v[26:27], v[10:11]
	v_mov_b64_e32 v[24:25], v[8:9]
	v_mov_b64_e32 v[22:23], v[6:7]
	v_mov_b64_e32 v[20:21], v[4:5]
	v_mov_b64_e32 v[18:19], v[2:3]
	v_mov_b64_e32 v[16:17], v[0:1]
	v_mov_b64_e32 v[92:93], v[12:13]
	v_mov_b64_e32 v[90:91], v[10:11]
	v_mov_b64_e32 v[88:89], v[8:9]
	v_mov_b64_e32 v[86:87], v[6:7]
	v_mov_b64_e32 v[84:85], v[4:5]
	v_mov_b64_e32 v[82:83], v[2:3]
	v_mov_b64_e32 v[80:81], v[0:1]
	v_mov_b64_e32 v[108:109], v[12:13]
	v_mov_b64_e32 v[106:107], v[10:11]
	v_mov_b64_e32 v[104:105], v[8:9]
	v_mov_b64_e32 v[102:103], v[6:7]
	v_mov_b64_e32 v[100:101], v[4:5]
	v_mov_b64_e32 v[98:99], v[2:3]
	v_mov_b64_e32 v[96:97], v[0:1]
	s_waitcnt lgkmcnt(0)
	s_barrier
	s_waitcnt vmcnt(1)
	ds_write_b128 v194, v[222:225] offset:32768
	s_and_saveexec_b64 s[2:3], s[8:9]
	ds_write_b128 v195, v[226:229] offset:32768
	s_or_b64 exec, exec, s[2:3]
	v_readlane_b32 s22, v254, 37
	v_readlane_b32 s23, v254, 38
	v_mov_b32_e32 v186, 0
	s_branch .LBB0_883
